# P8 GEMM tile transition: store acknowledgements overlap the next tile's first two MFMA blocks (first-iteration vmcnt(8) waits skipped, full drain before the K loop removed)
# baseline (speedup 1.0000x reference)
; #define PG8_STAGE(bufoff, gbase, voff) do { _Pragma("unroll") for (int _i = 0; _i < 2; ++_i) \
;         __builtin_amdgcn_global_load_lds((const unsigned*)((const char*)(gbase) + (voff)[_i]), (PG8_LAS unsigned*)(lds + (bufoff) + ldsw + _i * 8192), 16, 0, 0); } while (0)
; #define PG8_LDA(dst, b, h) do { _Pragma("unroll") for (int m = 0; m < 4; ++m) _Pragma("unroll") for (int k = 0; k < 2; ++k) dst[m][k] = *(const PG8_LAS bf16x8*)(lds + PG8_SA(b, h) + aoff + m * 2048 + k * 1024); } while (0)
; #define PG8_LDB(dst, b, h) do { _Pragma("unroll") for (int n = 0; n < 2; ++n) _Pragma("unroll") for (int k = 0; k < 2; ++k) dst[n][k] = *(const PG8_LAS bf16x8*)(lds + PG8_SB(b, h) + boff + n * 2048 + k * 1024); } while (0)
; #define PG8_WAIT_V(n) asm volatile("s_waitcnt vmcnt(" #n ")" ::: "memory")
; template <class Epi, class Sched, bool ALIGN_EPI = false, bool SP2 = false>
; __device__ __forceinline__ void gemm_phase(PG8_LAS unsigned char* lds, const Gemm g, const Sched& S, const Epi& E) {
;     ...
;         const bool has_next = S.next(ui + 1, nxt);
;         const char* nA = has_next ? (const char*)g.A + (size_t)nxt.pm * tstep : cA; const char* nB = has_next ? (const char*)g.Bt + (size_t)nxt.pn * tstep : cB;
;         for (int t = 0; t < nt; t += 2) {
;             const bool last = (t == nt - 2);
;             const char* a1 = cA + (size_t)(t + 1) * kstep;
;             const char* a2 = last ? nA : cA + (size_t)(t + 2) * kstep; const char* b2 = last ? nB : cB + (size_t)(t + 2) * kstep;
;             const char* a3 = a2 + kstep; const char* b3 = b2 + kstep;
;             if (last && has_next) S.a_ready(nxt);
;             if constexpr (SP2) {
;             PG8_LDB(B0, 0, 0); PG8_LDB(B1, 0, 1); PG8_SCHED; PG8_LDA(At, 0, 0); PG8_STAGE(PG8_SA(1, 1), a1 + hstep, voffA);
;             PG8_WAIT_V(8); PG8_WAIT_L(0); PG8_BAR; PG8_MMA(0, 0, At, B0); PG8_MMA(0, 1, At, B1); PG8_BAR; PG8_SCHED;
;             PG8_LDA(At, 0, 1); PG8_STAGE(PG8_SB(0, 0), b2, voffB); PG8_STAGE(PG8_SB(0, 1), b2 + hstep, voffB); PG8_STAGE(PG8_SA(0, 0), a2, voffA);
;     ...
; #pragma unroll
;         for (int a = 0; a < 2; ++a)
; #pragma unroll
;             for (int b = 0; b < 2; ++b)
; #pragma unroll
;                 for (int m = 0; m < 4; ++m)
; #pragma unroll
;                     for (int n = 0; n < 2; ++n) acc[a][b][m][n] = (f32x4){0.f, 0.f, 0.f, 0.f};
;         cur = nxt; cA = nA; cB = nB; ++ui;
.LBB0_907:
	s_ashr_i32 s49, s48, 31
	s_lshl_b64 s[50:51], s[48:49], 20
	s_add_u32 s50, s12, s50
	s_addc_u32 s51, s13, s51
	s_and_b64 s[64:65], s[6:7], exec
	s_cselect_b32 s49, s51, s69
	s_cselect_b32 s82, s50, s68
	s_ashr_i32 s47, s46, 31
	s_lshl_b64 s[64:65], s[46:47], 20
	v_readlane_b32 s72, v253, 22
	v_readlane_b32 s73, v253, 23
	s_add_u32 s64, s72, s64
	s_addc_u32 s65, s73, s65
	s_and_b64 s[72:73], s[6:7], exec
	s_cselect_b32 s47, s65, s71
	s_cselect_b32 s83, s64, s70
	s_add_u32 s68, s68, 0x80080
	s_addc_u32 s69, s69, 0
	s_add_u32 s84, s70, 0x100
	v_mov_b32_e32 v2, 0
	s_addc_u32 s85, s71, 0
	s_mov_b32 s86, -2
	v_mov_b32_e32 v3, v2
	v_mov_b32_e32 v4, v2
	v_mov_b32_e32 v5, v2
	v_mov_b32_e32 v14, v2
	v_mov_b32_e32 v15, v2
	v_mov_b32_e32 v16, v2
	v_mov_b32_e32 v17, v2
	v_mov_b32_e32 v18, v2
	v_mov_b32_e32 v19, v2
	v_mov_b32_e32 v20, v2
	v_mov_b32_e32 v21, v2
	v_mov_b32_e32 v22, v2
	s_waitcnt lgkmcnt(0)
	v_mov_b32_e32 v23, v2
	v_mov_b32_e32 v24, v2
	v_mov_b32_e32 v25, v2
	v_mov_b32_e32 v34, v2
	v_mov_b32_e32 v35, v2
	v_mov_b32_e32 v36, v2
	v_mov_b32_e32 v37, v2
	v_mov_b32_e32 v38, v2
	v_mov_b32_e32 v39, v2
	v_mov_b32_e32 v40, v2
	v_mov_b32_e32 v41, v2
	v_mov_b32_e32 v50, v2
	v_mov_b32_e32 v51, v2
	v_mov_b32_e32 v52, v2
	v_mov_b32_e32 v53, v2
	v_mov_b32_e32 v54, v2
	v_mov_b32_e32 v55, v2
	v_mov_b32_e32 v56, v2
	v_mov_b32_e32 v57, v2
	v_mov_b32_e32 v6, v2
	v_mov_b32_e32 v7, v2
	v_mov_b32_e32 v8, v2
	v_mov_b32_e32 v9, v2
	v_mov_b32_e32 v10, v2
	v_mov_b32_e32 v11, v2
	v_mov_b32_e32 v12, v2
	v_mov_b32_e32 v13, v2
	v_mov_b32_e32 v26, v2
	v_mov_b32_e32 v27, v2
	v_mov_b32_e32 v28, v2
	v_mov_b32_e32 v29, v2
	v_mov_b32_e32 v30, v2
	v_mov_b32_e32 v31, v2
	v_mov_b32_e32 v32, v2
	v_mov_b32_e32 v33, v2
	v_mov_b32_e32 v42, v2
	v_mov_b32_e32 v43, v2
	v_mov_b32_e32 v44, v2
	v_mov_b32_e32 v45, v2
	v_mov_b32_e32 v46, v2
	v_mov_b32_e32 v47, v2
	v_mov_b32_e32 v48, v2
	v_mov_b32_e32 v49, v2
	v_mov_b32_e32 v58, v2
	v_mov_b32_e32 v59, v2
	v_mov_b32_e32 v60, v2
	v_mov_b32_e32 v61, v2
	v_mov_b32_e32 v62, v2
	v_mov_b32_e32 v63, v2
	v_mov_b32_e32 v64, v2
	v_mov_b32_e32 v65, v2
	v_mov_b32_e32 v66, v2
	v_mov_b32_e32 v67, v2
	v_mov_b32_e32 v68, v2
	v_mov_b32_e32 v69, v2
	v_mov_b32_e32 v74, v2
	v_mov_b32_e32 v75, v2
	v_mov_b32_e32 v76, v2
	v_mov_b32_e32 v77, v2
	v_mov_b32_e32 v114, v2
	v_mov_b32_e32 v115, v2
	v_mov_b32_e32 v116, v2
	v_mov_b32_e32 v117, v2
	v_mov_b32_e32 v118, v2
	v_mov_b32_e32 v119, v2
	v_mov_b32_e32 v120, v2
	v_mov_b32_e32 v121, v2
	v_mov_b32_e32 v130, v2
	v_mov_b32_e32 v131, v2
	v_mov_b32_e32 v132, v2
	v_mov_b32_e32 v133, v2
	v_mov_b32_e32 v134, v2
	v_mov_b32_e32 v135, v2
	v_mov_b32_e32 v136, v2
	v_mov_b32_e32 v137, v2
	v_mov_b32_e32 v146, v2
	v_mov_b32_e32 v147, v2
	v_mov_b32_e32 v148, v2
	v_mov_b32_e32 v149, v2
	v_mov_b32_e32 v150, v2
	v_mov_b32_e32 v151, v2
	v_mov_b32_e32 v152, v2
	v_mov_b32_e32 v153, v2
	v_mov_b32_e32 v70, v2
	v_mov_b32_e32 v71, v2
	v_mov_b32_e32 v72, v2
	v_mov_b32_e32 v73, v2
	v_mov_b32_e32 v78, v2
	v_mov_b32_e32 v79, v2
	v_mov_b32_e32 v80, v2
	v_mov_b32_e32 v81, v2
	v_mov_b32_e32 v122, v2
	v_mov_b32_e32 v123, v2
	v_mov_b32_e32 v124, v2
	v_mov_b32_e32 v125, v2
	v_mov_b32_e32 v126, v2
	v_mov_b32_e32 v127, v2
	v_mov_b32_e32 v128, v2
	v_mov_b32_e32 v129, v2
	v_mov_b32_e32 v138, v2
	v_mov_b32_e32 v139, v2
	v_mov_b32_e32 v140, v2
	v_mov_b32_e32 v141, v2
	v_mov_b32_e32 v142, v2
	v_mov_b32_e32 v143, v2
	v_mov_b32_e32 v144, v2
	v_mov_b32_e32 v145, v2
	v_mov_b32_e32 v154, v2
	v_mov_b32_e32 v155, v2
	v_mov_b32_e32 v156, v2
	v_mov_b32_e32 v157, v2
	v_mov_b32_e32 v158, v2
	v_mov_b32_e32 v159, v2
	v_mov_b32_e32 v160, v2
	v_mov_b32_e32 v161, v2
	s_nop 0
.LBB0_908:
	ds_read_b128 v[82:85], v207
	ds_read_b128 v[86:89], v207 offset:1024
	ds_read_b128 v[90:93], v207 offset:2048
	ds_read_b128 v[94:97], v207 offset:3072
	ds_read_b128 v[98:101], v208
	ds_read_b128 v[102:105], v208 offset:1024
	ds_read_b128 v[106:109], v208 offset:2048
	ds_read_b128 v[110:113], v208 offset:3072
	s_add_u32 s70, s68, 0xfff80080
	s_addc_u32 s71, s69, -1
	s_cmp_eq_u32 s86, 28
	s_cselect_b32 s73, s49, s71
	s_cselect_b32 s72, s82, s70
	s_cselect_b32 s71, s47, s85
	s_cselect_b32 s70, s83, s84
	v_lshl_add_u64 v[228:229], s[68:69], 0, v[178:179]
	s_add_i32 m0, s35, 0xc000
	ds_read_b128 v[186:189], v209
	ds_read_b128 v[190:193], v209 offset:1024
	ds_read_b128 v[194:197], v209 offset:2048
	ds_read_b128 v[198:201], v209 offset:3072
	ds_read_b128 v[202:205], v209 offset:4096
	ds_read_b128 v[216:219], v209 offset:5120
	ds_read_b128 v[220:223], v209 offset:6144
	ds_read_b128 v[224:227], v209 offset:7168
	global_load_lds_dwordx4 v[228:229], off
	v_lshl_add_u64 v[228:229], s[68:69], 0, v[180:181]
	s_add_i32 m0, s35, 0xe000
	s_nop 0
	global_load_lds_dwordx4 v[228:229], off
	s_cmp_eq_u32 s86, 0
	s_cbranch_scc1 .Ldrn0_0
	s_waitcnt vmcnt(8)
; #define PG8_STAGE(bufoff, gbase, voff) do { _Pragma("unroll") for (int _i = 0; _i < 2; ++_i) \
;         __builtin_amdgcn_global_load_lds((const unsigned*)((const char*)(gbase) + (voff)[_i]), (PG8_LAS unsigned*)(lds + (bufoff) + ldsw + _i * 8192), 16, 0, 0); } while (0)
; #define PG8_LDA(dst, b, h) do { _Pragma("unroll") for (int m = 0; m < 4; ++m) _Pragma("unroll") for (int k = 0; k < 2; ++k) dst[m][k] = *(const PG8_LAS bf16x8*)(lds + PG8_SA(b, h) + aoff + m * 2048 + k * 1024); } while (0)
; #define PG8_MMA(ai, bj, At, Bt) do { __builtin_amdgcn_s_setprio(1); _Pragma("unroll") for (int m = 0; m < 4; ++m) _Pragma("unroll") for (int n = 0; n < 2; ++n) _Pragma("unroll") for (int k = 0; k < 2; ++k) \
;         acc[ai][bj][m][n] = __builtin_amdgcn_mfma_f32_16x16x32_bf16(Bt[n][k], At[m][k], acc[ai][bj][m][n], 0, 0, 0); __builtin_amdgcn_s_setprio(0); } while (0)
; #define PG8_WAIT_V(n) asm volatile("s_waitcnt vmcnt(" #n ")" ::: "memory")
; #define PG8_WAIT_L(n) asm volatile("s_waitcnt lgkmcnt(" #n ")" ::: "memory")
; #define PG8_BAR __builtin_amdgcn_s_barrier()
; #define PG8_SCHED __builtin_amdgcn_sched_barrier(0)
; template <class Epi, class Sched, bool ALIGN_EPI = false, bool SP2 = false>
; __device__ __forceinline__ void gemm_phase(PG8_LAS unsigned char* lds, const Gemm g, const Sched& S, const Epi& E) {
;     ...
;             PG8_WAIT_V(8); PG8_WAIT_L(0); PG8_BAR; PG8_MMA(0, 0, At, B0); PG8_MMA(0, 1, At, B1); PG8_BAR; PG8_SCHED;
;             PG8_LDA(At, 0, 1); PG8_STAGE(PG8_SB(0, 0), b2, voffB); PG8_STAGE(PG8_SB(0, 1), b2 + hstep, voffB); PG8_STAGE(PG8_SA(0, 0), a2, voffA);
;             PG8_WAIT_V(8); PG8_WAIT_L(0); PG8_BAR; PG8_MMA(1, 0, At, B0); PG8_MMA(1, 1, At, B1); PG8_BAR; PG8_SCHED;
.Ldrn0_0:
	s_waitcnt lgkmcnt(0)
	s_barrier
	s_setprio 1
	s_waitcnt lgkmcnt(0)
	v_mfma_f32_16x16x32_bf16 v[158:161], v[82:85], v[186:189], v[158:161]
	v_mfma_f32_16x16x32_bf16 v[154:157], v[90:93], v[186:189], v[154:157]
	v_mfma_f32_16x16x32_bf16 v[142:145], v[82:85], v[194:197], v[142:145]
	v_mfma_f32_16x16x32_bf16 v[138:141], v[90:93], v[194:197], v[138:141]
	v_mfma_f32_16x16x32_bf16 v[126:129], v[82:85], v[202:205], v[126:129]
	v_mfma_f32_16x16x32_bf16 v[122:125], v[90:93], v[202:205], v[122:125]
	v_mfma_f32_16x16x32_bf16 v[78:81], v[82:85], v[220:223], v[78:81]
	v_mfma_f32_16x16x32_bf16 v[70:73], v[90:93], v[220:223], v[70:73]
	v_mfma_f32_16x16x32_bf16 v[158:161], v[86:89], v[190:193], v[158:161]
	v_mfma_f32_16x16x32_bf16 v[154:157], v[94:97], v[190:193], v[154:157]
	v_mfma_f32_16x16x32_bf16 v[142:145], v[86:89], v[198:201], v[142:145]
	v_mfma_f32_16x16x32_bf16 v[138:141], v[94:97], v[198:201], v[138:141]
	v_mfma_f32_16x16x32_bf16 v[126:129], v[86:89], v[216:219], v[126:129]
	v_mfma_f32_16x16x32_bf16 v[122:125], v[94:97], v[216:219], v[122:125]
	v_mfma_f32_16x16x32_bf16 v[78:81], v[86:89], v[224:227], v[78:81]
	v_mfma_f32_16x16x32_bf16 v[70:73], v[94:97], v[224:227], v[70:73]
	s_setprio 0
	s_setprio 1
	v_mfma_f32_16x16x32_bf16 v[150:153], v[98:101], v[186:189], v[150:153]
	v_mfma_f32_16x16x32_bf16 v[146:149], v[106:109], v[186:189], v[146:149]
	v_mfma_f32_16x16x32_bf16 v[134:137], v[98:101], v[194:197], v[134:137]
	v_mfma_f32_16x16x32_bf16 v[130:133], v[106:109], v[194:197], v[130:133]
	v_mfma_f32_16x16x32_bf16 v[118:121], v[98:101], v[202:205], v[118:121]
	v_mfma_f32_16x16x32_bf16 v[114:117], v[106:109], v[202:205], v[114:117]
	v_mfma_f32_16x16x32_bf16 v[74:77], v[98:101], v[220:223], v[74:77]
	v_mfma_f32_16x16x32_bf16 v[66:69], v[106:109], v[220:223], v[66:69]
	v_mfma_f32_16x16x32_bf16 v[150:153], v[102:105], v[190:193], v[150:153]
	v_mfma_f32_16x16x32_bf16 v[146:149], v[110:113], v[190:193], v[146:149]
	v_mfma_f32_16x16x32_bf16 v[134:137], v[102:105], v[198:201], v[134:137]
	v_mfma_f32_16x16x32_bf16 v[130:133], v[110:113], v[198:201], v[130:133]
	v_mfma_f32_16x16x32_bf16 v[118:121], v[102:105], v[216:219], v[118:121]
	v_mfma_f32_16x16x32_bf16 v[114:117], v[110:113], v[216:219], v[114:117]
	v_mfma_f32_16x16x32_bf16 v[74:77], v[102:105], v[224:227], v[74:77]
	v_mfma_f32_16x16x32_bf16 v[66:69], v[110:113], v[224:227], v[66:69]
	s_setprio 0
	s_barrier
	s_add_i32 s87, s75, s16
	v_lshl_add_u64 v[228:229], s[70:71], 0, v[170:171]
	s_mov_b32 m0, s87
	ds_read_b128 v[186:189], v209 offset:16384
	ds_read_b128 v[190:193], v209 offset:17408
	ds_read_b128 v[194:197], v209 offset:18432
	ds_read_b128 v[198:201], v209 offset:19456
	ds_read_b128 v[202:205], v209 offset:20480
	ds_read_b128 v[216:219], v209 offset:21504
	ds_read_b128 v[220:223], v209 offset:22528
	ds_read_b128 v[224:227], v209 offset:23552
	global_load_lds_dwordx4 v[228:229], off
	s_add_i32 m0, s87, 0x2000
	s_add_u32 s88, s70, 0x80000
	v_lshl_add_u64 v[230:231], s[70:71], 0, v[166:167]
	s_addc_u32 s89, s71, 0
	s_add_i32 s87, s76, s16
	global_load_lds_dwordx4 v[230:231], off
	v_lshl_add_u64 v[232:233], s[88:89], 0, v[170:171]
	s_mov_b32 m0, s87
	v_lshl_add_u64 v[234:235], s[72:73], 0, v[168:169]
	global_load_lds_dwordx4 v[232:233], off
	v_lshl_add_u64 v[232:233], s[88:89], 0, v[166:167]
	s_add_i32 m0, s87, 0x2000
	s_nop 0
	global_load_lds_dwordx4 v[232:233], off
	v_lshl_add_u64 v[232:233], s[72:73], 0, v[172:173]
	s_mov_b32 m0, s35
	s_nop 0
	global_load_lds_dwordx4 v[232:233], off
	s_mov_b32 m0, s57
	s_nop 0
	global_load_lds_dwordx4 v[234:235], off
	s_cmp_eq_u32 s86, 0
	s_cbranch_scc1 .Ldrn0_1
	s_waitcnt vmcnt(8)
.Ldrn0_1:
	s_waitcnt lgkmcnt(0)
	s_barrier
	s_setprio 1
	s_waitcnt lgkmcnt(0)
	v_mfma_f32_16x16x32_bf16 v[62:65], v[82:85], v[186:189], v[62:65]
	v_mfma_f32_16x16x32_bf16 v[58:61], v[90:93], v[186:189], v[58:61]
	v_mfma_f32_16x16x32_bf16 v[46:49], v[82:85], v[194:197], v[46:49]
	v_mfma_f32_16x16x32_bf16 v[42:45], v[90:93], v[194:197], v[42:45]
	v_mfma_f32_16x16x32_bf16 v[30:33], v[82:85], v[202:205], v[30:33]
	v_mfma_f32_16x16x32_bf16 v[26:29], v[90:93], v[202:205], v[26:29]
	v_mfma_f32_16x16x32_bf16 v[10:13], v[82:85], v[220:223], v[10:13]
	v_mfma_f32_16x16x32_bf16 v[6:9], v[90:93], v[220:223], v[6:9]
	v_mfma_f32_16x16x32_bf16 v[62:65], v[86:89], v[190:193], v[62:65]
	v_mfma_f32_16x16x32_bf16 v[58:61], v[94:97], v[190:193], v[58:61]
	v_mfma_f32_16x16x32_bf16 v[46:49], v[86:89], v[198:201], v[46:49]
	v_mfma_f32_16x16x32_bf16 v[42:45], v[94:97], v[198:201], v[42:45]
	v_mfma_f32_16x16x32_bf16 v[30:33], v[86:89], v[216:219], v[30:33]
	v_mfma_f32_16x16x32_bf16 v[26:29], v[94:97], v[216:219], v[26:29]
	v_mfma_f32_16x16x32_bf16 v[10:13], v[86:89], v[224:227], v[10:13]
	v_mfma_f32_16x16x32_bf16 v[6:9], v[94:97], v[224:227], v[6:9]
	s_setprio 0
	s_setprio 1
	v_mfma_f32_16x16x32_bf16 v[54:57], v[98:101], v[186:189], v[54:57]
	v_mfma_f32_16x16x32_bf16 v[50:53], v[106:109], v[186:189], v[50:53]
	v_mfma_f32_16x16x32_bf16 v[38:41], v[98:101], v[194:197], v[38:41]
	v_mfma_f32_16x16x32_bf16 v[34:37], v[106:109], v[194:197], v[34:37]
	v_mfma_f32_16x16x32_bf16 v[22:25], v[98:101], v[202:205], v[22:25]
	v_mfma_f32_16x16x32_bf16 v[18:21], v[106:109], v[202:205], v[18:21]
	v_mfma_f32_16x16x32_bf16 v[14:17], v[98:101], v[220:223], v[14:17]
	v_mfma_f32_16x16x32_bf16 v[2:5], v[106:109], v[220:223], v[2:5]
	v_mfma_f32_16x16x32_bf16 v[54:57], v[102:105], v[190:193], v[54:57]
	v_mfma_f32_16x16x32_bf16 v[50:53], v[110:113], v[190:193], v[50:53]
	v_mfma_f32_16x16x32_bf16 v[38:41], v[102:105], v[198:201], v[38:41]
	v_mfma_f32_16x16x32_bf16 v[34:37], v[110:113], v[198:201], v[34:37]
	v_mfma_f32_16x16x32_bf16 v[22:25], v[102:105], v[216:219], v[22:25]
	v_mfma_f32_16x16x32_bf16 v[18:21], v[110:113], v[216:219], v[18:21]
	v_mfma_f32_16x16x32_bf16 v[14:17], v[102:105], v[224:227], v[14:17]
	v_mfma_f32_16x16x32_bf16 v[2:5], v[110:113], v[224:227], v[2:5]
	s_setprio 0
	s_barrier
; #define PG8_STAGE(bufoff, gbase, voff) do { _Pragma("unroll") for (int _i = 0; _i < 2; ++_i) \
;         __builtin_amdgcn_global_load_lds((const unsigned*)((const char*)(gbase) + (voff)[_i]), (PG8_LAS unsigned*)(lds + (bufoff) + ldsw + _i * 8192), 16, 0, 0); } while (0)
; #define PG8_LDA(dst, b, h) do { _Pragma("unroll") for (int m = 0; m < 4; ++m) _Pragma("unroll") for (int k = 0; k < 2; ++k) dst[m][k] = *(const PG8_LAS bf16x8*)(lds + PG8_SA(b, h) + aoff + m * 2048 + k * 1024); } while (0)
; #define PG8_LDB(dst, b, h) do { _Pragma("unroll") for (int n = 0; n < 2; ++n) _Pragma("unroll") for (int k = 0; k < 2; ++k) dst[n][k] = *(const PG8_LAS bf16x8*)(lds + PG8_SB(b, h) + boff + n * 2048 + k * 1024); } while (0)
; #define PG8_MMA(ai, bj, At, Bt) do { __builtin_amdgcn_s_setprio(1); _Pragma("unroll") for (int m = 0; m < 4; ++m) _Pragma("unroll") for (int n = 0; n < 2; ++n) _Pragma("unroll") for (int k = 0; k < 2; ++k) \
;         acc[ai][bj][m][n] = __builtin_amdgcn_mfma_f32_16x16x32_bf16(Bt[n][k], At[m][k], acc[ai][bj][m][n], 0, 0, 0); __builtin_amdgcn_s_setprio(0); } while (0)
; #define PG8_WAIT_V(n) asm volatile("s_waitcnt vmcnt(" #n ")" ::: "memory")
; #define PG8_WAIT_L(n) asm volatile("s_waitcnt lgkmcnt(" #n ")" ::: "memory")
; #define PG8_BAR __builtin_amdgcn_s_barrier()
; #define PG8_SCHED __builtin_amdgcn_sched_barrier(0)
; template <class Epi, class Sched, bool ALIGN_EPI = false, bool SP2 = false>
; __device__ __forceinline__ void gemm_phase(PG8_LAS unsigned char* lds, const Gemm g, const Sched& S, const Epi& E) {
;     ...
;             PG8_LDB(B0, 1, 0); PG8_LDB(B1, 1, 1); PG8_SCHED; PG8_LDA(At, 1, 0); PG8_STAGE(PG8_SA(0, 1), a2 + hstep, voffA);
;             PG8_WAIT_V(8); PG8_WAIT_L(0); PG8_BAR; PG8_MMA(0, 0, At, B0); PG8_MMA(0, 1, At, B1); PG8_BAR; PG8_SCHED;
	ds_read_b128 v[82:85], v210
	ds_read_b128 v[86:89], v210 offset:1024
	ds_read_b128 v[90:93], v210 offset:2048
	ds_read_b128 v[94:97], v210 offset:3072
	ds_read_b128 v[98:101], v211
	ds_read_b128 v[102:105], v211 offset:1024
	ds_read_b128 v[106:109], v211 offset:2048
	ds_read_b128 v[110:113], v211 offset:3072
	s_add_u32 s72, s72, 0x80000
	s_addc_u32 s73, s73, 0
	s_mov_b32 m0, s58
	v_lshl_add_u64 v[236:237], s[72:73], 0, v[172:173]
	ds_read_b128 v[186:189], v209 offset:32768
	ds_read_b128 v[190:193], v209 offset:33792
	ds_read_b128 v[194:197], v209 offset:34816
	ds_read_b128 v[198:201], v209 offset:35840
	ds_read_b128 v[202:205], v209 offset:36864
	ds_read_b128 v[216:219], v209 offset:37888
	ds_read_b128 v[220:223], v209 offset:38912
	ds_read_b128 v[224:227], v209 offset:39936
	global_load_lds_dwordx4 v[236:237], off
	v_lshl_add_u64 v[236:237], s[72:73], 0, v[168:169]
	s_mov_b32 m0, s59
	s_nop 0
	global_load_lds_dwordx4 v[236:237], off
	s_waitcnt vmcnt(8)
	s_waitcnt lgkmcnt(0)
	s_barrier
	s_setprio 1
	s_waitcnt lgkmcnt(0)
	v_mfma_f32_16x16x32_bf16 v[158:161], v[82:85], v[186:189], v[158:161]
	v_mfma_f32_16x16x32_bf16 v[154:157], v[90:93], v[186:189], v[154:157]
	v_mfma_f32_16x16x32_bf16 v[142:145], v[82:85], v[194:197], v[142:145]
	v_mfma_f32_16x16x32_bf16 v[138:141], v[90:93], v[194:197], v[138:141]
	v_mfma_f32_16x16x32_bf16 v[126:129], v[82:85], v[202:205], v[126:129]
	v_mfma_f32_16x16x32_bf16 v[122:125], v[90:93], v[202:205], v[122:125]
	v_mfma_f32_16x16x32_bf16 v[78:81], v[82:85], v[220:223], v[78:81]
	v_mfma_f32_16x16x32_bf16 v[70:73], v[90:93], v[220:223], v[70:73]
	v_mfma_f32_16x16x32_bf16 v[158:161], v[86:89], v[190:193], v[158:161]
	v_mfma_f32_16x16x32_bf16 v[154:157], v[94:97], v[190:193], v[154:157]
	v_mfma_f32_16x16x32_bf16 v[142:145], v[86:89], v[198:201], v[142:145]
	v_mfma_f32_16x16x32_bf16 v[138:141], v[94:97], v[198:201], v[138:141]
	v_mfma_f32_16x16x32_bf16 v[126:129], v[86:89], v[216:219], v[126:129]
	v_mfma_f32_16x16x32_bf16 v[122:125], v[94:97], v[216:219], v[122:125]
	v_mfma_f32_16x16x32_bf16 v[78:81], v[86:89], v[224:227], v[78:81]
	v_mfma_f32_16x16x32_bf16 v[70:73], v[94:97], v[224:227], v[70:73]
	s_setprio 0
	s_setprio 1
	v_mfma_f32_16x16x32_bf16 v[150:153], v[98:101], v[186:189], v[150:153]
	v_mfma_f32_16x16x32_bf16 v[146:149], v[106:109], v[186:189], v[146:149]
	v_mfma_f32_16x16x32_bf16 v[134:137], v[98:101], v[194:197], v[134:137]
	v_mfma_f32_16x16x32_bf16 v[130:133], v[106:109], v[194:197], v[130:133]
	v_mfma_f32_16x16x32_bf16 v[118:121], v[98:101], v[202:205], v[118:121]
	v_mfma_f32_16x16x32_bf16 v[114:117], v[106:109], v[202:205], v[114:117]
	v_mfma_f32_16x16x32_bf16 v[74:77], v[98:101], v[220:223], v[74:77]
	v_mfma_f32_16x16x32_bf16 v[66:69], v[106:109], v[220:223], v[66:69]
	v_mfma_f32_16x16x32_bf16 v[150:153], v[102:105], v[190:193], v[150:153]
	v_mfma_f32_16x16x32_bf16 v[146:149], v[110:113], v[190:193], v[146:149]
	v_mfma_f32_16x16x32_bf16 v[134:137], v[102:105], v[198:201], v[134:137]
	v_mfma_f32_16x16x32_bf16 v[130:133], v[110:113], v[198:201], v[130:133]
	v_mfma_f32_16x16x32_bf16 v[118:121], v[102:105], v[216:219], v[118:121]
	v_mfma_f32_16x16x32_bf16 v[114:117], v[110:113], v[216:219], v[114:117]
	v_mfma_f32_16x16x32_bf16 v[74:77], v[102:105], v[224:227], v[74:77]
	v_mfma_f32_16x16x32_bf16 v[66:69], v[110:113], v[224:227], v[66:69]
	s_setprio 0
	s_barrier
; #define PG8_STAGE(bufoff, gbase, voff) do { _Pragma("unroll") for (int _i = 0; _i < 2; ++_i) \
;         __builtin_amdgcn_global_load_lds((const unsigned*)((const char*)(gbase) + (voff)[_i]), (PG8_LAS unsigned*)(lds + (bufoff) + ldsw + _i * 8192), 16, 0, 0); } while (0)
; #define PG8_LDA(dst, b, h) do { _Pragma("unroll") for (int m = 0; m < 4; ++m) _Pragma("unroll") for (int k = 0; k < 2; ++k) dst[m][k] = *(const PG8_LAS bf16x8*)(lds + PG8_SA(b, h) + aoff + m * 2048 + k * 1024); } while (0)
; #define PG8_WAIT_V(n) asm volatile("s_waitcnt vmcnt(" #n ")" ::: "memory")
; template <class Epi, class Sched, bool ALIGN_EPI = false, bool SP2 = false>
; __device__ __forceinline__ void gemm_phase(PG8_LAS unsigned char* lds, const Gemm g, const Sched& S, const Epi& E) {
;     ...
;             PG8_LDA(At, 1, 1); PG8_STAGE(PG8_SB(1, 0), b3, voffB); PG8_STAGE(PG8_SB(1, 1), b3 + hstep, voffB); PG8_STAGE(PG8_SA(1, 0), a3, voffA);
;             PG8_WAIT_V(8); PG8_WAIT_L(0); PG8_BAR; PG8_MMA(1, 0, At, B0); PG8_MMA(1, 1, At, B1); PG8_BAR; PG8_SCHED;
;             } else {
;             PG8_LDB(B0, 0, 0); PG8_SCHED; PG8_LDA(At, 0, 0); PG8_STAGE(PG8_SA(1, 1), a1 + hstep, voffA);
;             PG8_WAIT_L(8); PG8_BAR; PG8_WAIT_L(0); PG8_MMA(0, 0, At, B0); PG8_BAR; PG8_SCHED;
;             PG8_LDB(B1, 0, 1); PG8_STAGE(PG8_SB(0, 0), b2, voffB);
;             PG8_BAR; PG8_WAIT_L(0); PG8_MMA(0, 1, At, B1); PG8_BAR;
;             PG8_LDA(At, 0, 1); PG8_STAGE(PG8_SA(0, 0), a2, voffA);
;             PG8_BAR; PG8_WAIT_L(0); PG8_MMA(1, 0, At, B0); PG8_BAR; PG8_SCHED;
;             PG8_STAGE(PG8_SB(0, 1), b2 + hstep, voffB);
;             PG8_WAIT_V(6); PG8_BAR; PG8_MMA(1, 1, At, B1); PG8_BAR;
;             PG8_LDB(B0, 1, 0); PG8_SCHED; PG8_LDA(At, 1, 0); PG8_STAGE(PG8_SA(0, 1), a2 + hstep, voffA);
;             PG8_WAIT_L(8); PG8_BAR; PG8_WAIT_L(0); PG8_MMA(0, 0, At, B0); PG8_BAR; PG8_SCHED;
;             PG8_LDB(B1, 1, 1); PG8_STAGE(PG8_SB(1, 0), b3, voffB);
;             PG8_BAR; PG8_WAIT_L(0); PG8_MMA(0, 1, At, B1); PG8_BAR;
;             PG8_LDA(At, 1, 1); PG8_STAGE(PG8_SA(1, 0), a3, voffA);
;             PG8_BAR; PG8_WAIT_L(0); PG8_MMA(1, 0, At, B0); PG8_BAR; PG8_SCHED;
;             PG8_STAGE(PG8_SB(1, 1), b3 + hstep, voffB);
;             PG8_WAIT_V(6); PG8_BAR; PG8_MMA(1, 1, At, B1); PG8_BAR;
;             }
;         }
;         if constexpr (ALIGN_EPI) { if (wr == 0) PG8_BAR; }
	s_add_i32 s72, s77, s16
	v_lshl_add_u64 v[228:229], v[228:229], 0, s[28:29]
	s_mov_b32 m0, s72
	ds_read_b128 v[186:189], v209 offset:49152
	ds_read_b128 v[190:193], v209 offset:50176
	ds_read_b128 v[194:197], v209 offset:51200
	ds_read_b128 v[198:201], v209 offset:52224
	ds_read_b128 v[202:205], v209 offset:53248
	ds_read_b128 v[216:219], v209 offset:54272
	ds_read_b128 v[220:223], v209 offset:55296
	ds_read_b128 v[224:227], v209 offset:56320
	global_load_lds_dwordx4 v[228:229], off
	s_add_i32 m0, s72, 0x2000
	s_add_u32 s70, s70, 0x80080
	v_lshl_add_u64 v[228:229], v[230:231], 0, s[28:29]
	s_addc_u32 s71, s71, 0
	s_add_i32 s72, s78, s16
	global_load_lds_dwordx4 v[228:229], off
	v_lshl_add_u64 v[228:229], s[70:71], 0, v[170:171]
	s_mov_b32 m0, s72
	s_nop 0
	global_load_lds_dwordx4 v[228:229], off
	v_lshl_add_u64 v[228:229], s[70:71], 0, v[166:167]
	s_add_i32 m0, s72, 0x2000
	s_nop 0
	global_load_lds_dwordx4 v[228:229], off
	v_lshl_add_u64 v[228:229], v[232:233], 0, s[28:29]
	s_mov_b32 m0, s61
	s_nop 0
	global_load_lds_dwordx4 v[228:229], off
	v_lshl_add_u64 v[228:229], v[234:235], 0, s[28:29]
	s_mov_b32 m0, s62
	s_nop 0
	global_load_lds_dwordx4 v[228:229], off
	s_waitcnt vmcnt(8)
	s_waitcnt lgkmcnt(0)
	s_barrier
	s_setprio 1
	s_waitcnt lgkmcnt(0)
	v_mfma_f32_16x16x32_bf16 v[62:65], v[82:85], v[186:189], v[62:65]
	v_mfma_f32_16x16x32_bf16 v[58:61], v[90:93], v[186:189], v[58:61]
	v_mfma_f32_16x16x32_bf16 v[46:49], v[82:85], v[194:197], v[46:49]
	v_mfma_f32_16x16x32_bf16 v[42:45], v[90:93], v[194:197], v[42:45]
	v_mfma_f32_16x16x32_bf16 v[30:33], v[82:85], v[202:205], v[30:33]
	v_mfma_f32_16x16x32_bf16 v[26:29], v[90:93], v[202:205], v[26:29]
	v_mfma_f32_16x16x32_bf16 v[10:13], v[82:85], v[220:223], v[10:13]
	v_mfma_f32_16x16x32_bf16 v[6:9], v[90:93], v[220:223], v[6:9]
	v_mfma_f32_16x16x32_bf16 v[62:65], v[86:89], v[190:193], v[62:65]
	v_mfma_f32_16x16x32_bf16 v[58:61], v[94:97], v[190:193], v[58:61]
	v_mfma_f32_16x16x32_bf16 v[46:49], v[86:89], v[198:201], v[46:49]
	v_mfma_f32_16x16x32_bf16 v[42:45], v[94:97], v[198:201], v[42:45]
	v_mfma_f32_16x16x32_bf16 v[30:33], v[86:89], v[216:219], v[30:33]
	v_mfma_f32_16x16x32_bf16 v[26:29], v[94:97], v[216:219], v[26:29]
	v_mfma_f32_16x16x32_bf16 v[10:13], v[86:89], v[224:227], v[10:13]
	v_mfma_f32_16x16x32_bf16 v[6:9], v[94:97], v[224:227], v[6:9]
	s_setprio 0
	s_setprio 1
	v_mfma_f32_16x16x32_bf16 v[54:57], v[98:101], v[186:189], v[54:57]
	v_mfma_f32_16x16x32_bf16 v[50:53], v[106:109], v[186:189], v[50:53]
	v_mfma_f32_16x16x32_bf16 v[38:41], v[98:101], v[194:197], v[38:41]
	v_mfma_f32_16x16x32_bf16 v[34:37], v[106:109], v[194:197], v[34:37]
	v_mfma_f32_16x16x32_bf16 v[22:25], v[98:101], v[202:205], v[22:25]
	v_mfma_f32_16x16x32_bf16 v[18:21], v[106:109], v[202:205], v[18:21]
	v_mfma_f32_16x16x32_bf16 v[14:17], v[98:101], v[220:223], v[14:17]
	v_mfma_f32_16x16x32_bf16 v[2:5], v[106:109], v[220:223], v[2:5]
	v_mfma_f32_16x16x32_bf16 v[54:57], v[102:105], v[190:193], v[54:57]
	v_mfma_f32_16x16x32_bf16 v[50:53], v[110:113], v[190:193], v[50:53]
	v_mfma_f32_16x16x32_bf16 v[38:41], v[102:105], v[198:201], v[38:41]
	v_mfma_f32_16x16x32_bf16 v[34:37], v[110:113], v[198:201], v[34:37]
	v_mfma_f32_16x16x32_bf16 v[22:25], v[102:105], v[216:219], v[22:25]
	v_mfma_f32_16x16x32_bf16 v[18:21], v[110:113], v[216:219], v[18:21]
	v_mfma_f32_16x16x32_bf16 v[14:17], v[102:105], v[224:227], v[14:17]
	v_mfma_f32_16x16x32_bf16 v[2:5], v[110:113], v[224:227], v[2:5]
	s_setprio 0
	s_barrier
	s_add_i32 s86, s86, 2
	s_add_u32 s68, s68, 0x100
	s_addc_u32 s69, s69, 0
	s_add_u32 s84, s84, 0x100
	s_addc_u32 s85, s85, 0
	s_cmp_gt_u32 s86, 29
	s_cbranch_scc0 .LBB0_908
	s_and_b64 vcc, exec, s[38:39]
	s_cbranch_vccz .LBB0_911
	s_barrier
